# MLA softmax trimmed (no negm copies, 3-chain max, in-place exp) + scalar staging addresses + counted vmcnt; attn0 bias/mask branch-free
# speedup vs baseline: 1.0137x; 1.0137x over previous
; template <int MODE>
; __device__ __forceinline__ void attn_unit(const Params& P, unsigned char* lds, int h, int rb, int grp, bool dry = false) {
;     ...
;             f32x16 p0 = {}, p1 = {};
;             const unsigned char* Kb = lds + A_K0 + buf * A_KBUF;
; #pragma unroll
;             for (int d0 = 0; d0 < ND; ++d0) { const int cb = (d0 * 16 + hi * 8) * 2;
;                 const bf16x8 b0 = *(const bf16x8*)(Kb + r32 * KSTR + cb), b1 = *(const bf16x8*)(Kb + (32 + r32) * KSTR + cb);
;                 p0 = __builtin_amdgcn_mfma_f32_32x32x16_bf16(b0, qr[d0], p0, 0, 0, 0);
;                 p1 = __builtin_amdgcn_mfma_f32_32x32x16_bf16(b1, qr[d0], p1, 0, 0, 0); }
;             if (MODE == 0) { const int dr = na_tlo + j - na_r; const float* tb = tab + (dr + 7) * 128 + (4 * hi - na_cq + 63); const int v = 4 * hi - na_cs;
; #pragma unroll
;                 for (int r = 0; r < 16; ++r) { const int c0 = (r & 3) + 8 * (r >> 2);
;                     p0[r] = ((unsigned)(c0 + v) < 16u) ? p0[r] + tb[c0] : -1e30f;
;                     p1[r] = ((unsigned)(c0 + 32 + v) < 16u) ? p1[r] + tb[c0 + 32] : -1e30f; } }
;             if (MODE == 1) { const int base = key0 + 64 * j - t0 + 4 * hi - 32 * wid - r32; const float* tb = tab + 512 + base;
; #pragma unroll
;                 for (int r = 0; r < 16; ++r) { const int c0 = (r & 3) + 8 * (r >> 2);
;                     p0[r] = ((unsigned)(base + c0 + 128) <= 256u) ? p0[r] + tb[c0] : -1e30f;
;                     p1[r] = ((unsigned)(base + c0 + 32 + 128) <= 256u) ? p1[r] + tb[c0 + 32] : -1e30f; } }
.LBB0_243:
	s_sub_i32 s3, s24, 63
	s_cmp_ge_i32 s24, s21
	s_cselect_b64 s[16:17], -1, 0
	s_cmp_le_i32 s3, s23
	s_cselect_b64 s[26:27], -1, 0
	s_and_b64 s[16:17], s[16:17], s[26:27]
	s_andn2_b64 vcc, exec, s[16:17]
	s_cbranch_vccnz .LBB0_313
	s_add_i32 s3, s22, -1
	s_and_b32 s3, s3, 1
	s_mul_i32 s16, s3, 0x3400
	v_add_u32_e32 v151, s16, v88
	ds_read_b32 v176, v148
	ds_read_b32 v177, v148 offset:128
	ds_read_b32 v178, v148 offset:4
	ds_read_b32 v179, v148 offset:132
	ds_read_b32 v180, v148 offset:8
	ds_read_b32 v181, v148 offset:136
	ds_read_b32 v182, v148 offset:12
	ds_read_b32 v183, v148 offset:140
	ds_read_b32 v184, v148 offset:32
	ds_read_b32 v185, v148 offset:160
	ds_read_b32 v186, v148 offset:36
	ds_read_b32 v187, v148 offset:164
	ds_read_b32 v188, v148 offset:40
	ds_read_b32 v189, v148 offset:168
	ds_read_b128 v[32:35], v151
	ds_read_b128 v[152:155], v151 offset:32
	s_waitcnt lgkmcnt(1)
	v_mfma_f32_32x32x16_bf16 v[48:63], v[32:35], v[64:67], 0
	ds_read_b128 v[32:35], v151 offset:6656
	ds_read_b128 v[156:159], v151 offset:6688
	s_waitcnt lgkmcnt(1)
	v_mfma_f32_32x32x16_bf16 v[32:47], v[32:35], v[64:67], 0
	v_mfma_f32_32x32x16_bf16 v[48:63], v[152:155], v[68:71], v[48:63]
	s_waitcnt lgkmcnt(0)
	v_mfma_f32_32x32x16_bf16 v[32:47], v[156:159], v[68:71], v[32:47]
	ds_read_b128 v[152:155], v151 offset:64
	ds_read_b128 v[156:159], v151 offset:96
	s_waitcnt lgkmcnt(1)
	v_mfma_f32_32x32x16_bf16 v[48:63], v[152:155], v[72:75], v[48:63]
	ds_read_b128 v[152:155], v151 offset:6720
	ds_read_b128 v[160:163], v151 offset:6752
	s_waitcnt lgkmcnt(1)
	v_mfma_f32_32x32x16_bf16 v[32:47], v[152:155], v[72:75], v[32:47]
	v_add_u32_e32 v154, s24, v147
	v_mfma_f32_32x32x16_bf16 v[48:63], v[156:159], v[76:79], v[48:63]
	s_waitcnt lgkmcnt(0)
	v_mfma_f32_32x32x16_bf16 v[32:47], v[160:163], v[76:79], v[32:47]
	v_mov_b32_e32 v208, 0xf149f2ca
	ds_read_b32 v190, v148 offset:44
	ds_read_b32 v191, v148 offset:172
	ds_read_b32 v192, v148 offset:64
	ds_read_b32 v193, v148 offset:192
	ds_read_b32 v194, v148 offset:68
	ds_read_b32 v195, v148 offset:196
	ds_read_b32 v196, v148 offset:72
	ds_read_b32 v197, v148 offset:200
	ds_read_b32 v198, v148 offset:76
	ds_read_b32 v199, v148 offset:204
	ds_read_b32 v200, v148 offset:96
	ds_read_b32 v201, v148 offset:224
	ds_read_b32 v202, v148 offset:100
	ds_read_b32 v203, v148 offset:228
	v_subrev_u32_e32 v209, 63, v154
	v_cmp_gt_u32_e32 vcc, s85, v209
	v_subrev_u32_e32 v210, 31, v154
	v_cmp_gt_u32_e64 s[98:99], s85, v210
	v_subrev_u32_e32 v211, 62, v154
	v_cmp_gt_u32_e64 s[100:101], s85, v211
	v_add_f32_e32 v176, v48, v176
	v_cndmask_b32_e32 v152, v208, v176, vcc
	v_subrev_u32_e32 v209, 30, v154
	v_cmp_gt_u32_e32 vcc, s85, v209
	v_add_f32_e32 v177, v32, v177
	v_cndmask_b32_e64 v151, v208, v177, s[98:99]
	v_subrev_u32_e32 v210, 61, v154
	v_cmp_gt_u32_e64 s[98:99], s85, v210
	v_add_f32_e32 v178, v49, v178
	v_cndmask_b32_e64 v153, v208, v178, s[100:101]
	v_subrev_u32_e32 v211, 29, v154
	v_cmp_gt_u32_e64 s[100:101], s85, v211
	v_add_f32_e32 v179, v33, v179
	v_cndmask_b32_e32 v48, v208, v179, vcc
	v_subrev_u32_e32 v209, 60, v154
	v_cmp_gt_u32_e32 vcc, s85, v209
	v_add_f32_e32 v180, v50, v180
	v_cndmask_b32_e64 v49, v208, v180, s[98:99]
	v_subrev_u32_e32 v210, 28, v154
	v_cmp_gt_u32_e64 s[98:99], s85, v210
	v_add_f32_e32 v181, v34, v181
	v_cndmask_b32_e64 v33, v208, v181, s[100:101]
	v_subrev_u32_e32 v211, 55, v154
	v_cmp_gt_u32_e64 s[100:101], s85, v211
	v_add_f32_e32 v182, v51, v182
	v_cndmask_b32_e32 v50, v208, v182, vcc
	v_subrev_u32_e32 v209, 23, v154
	v_cmp_gt_u32_e32 vcc, s85, v209
	v_add_f32_e32 v183, v35, v183
	v_cndmask_b32_e64 v34, v208, v183, s[98:99]
	v_subrev_u32_e32 v210, 54, v154
	v_cmp_gt_u32_e64 s[98:99], s85, v210
	v_add_f32_e32 v184, v52, v184
	v_cndmask_b32_e64 v51, v208, v184, s[100:101]
	v_subrev_u32_e32 v211, 22, v154
	v_cmp_gt_u32_e64 s[100:101], s85, v211
	v_add_f32_e32 v185, v36, v185
	v_cndmask_b32_e32 v35, v208, v185, vcc
	v_subrev_u32_e32 v209, 53, v154
	v_cmp_gt_u32_e32 vcc, s85, v209
	v_add_f32_e32 v186, v53, v186
	v_cndmask_b32_e64 v52, v208, v186, s[98:99]
	v_subrev_u32_e32 v210, 21, v154
	v_cmp_gt_u32_e64 s[98:99], s85, v210
	v_add_f32_e32 v187, v37, v187
	v_cndmask_b32_e64 v36, v208, v187, s[100:101]
	v_subrev_u32_e32 v211, 52, v154
	v_cmp_gt_u32_e64 s[100:101], s85, v211
	v_add_f32_e32 v188, v54, v188
	v_cndmask_b32_e32 v53, v208, v188, vcc
	v_subrev_u32_e32 v209, 20, v154
	v_cmp_gt_u32_e32 vcc, s85, v209
	v_add_f32_e32 v189, v38, v189
	v_cndmask_b32_e64 v37, v208, v189, s[98:99]
	s_waitcnt lgkmcnt(0)
	ds_read_b32 v204, v148 offset:104
	ds_read_b32 v205, v148 offset:232
	ds_read_b32 v206, v148 offset:108
	ds_read_b32 v207, v148 offset:236
	v_subrev_u32_e32 v210, 47, v154
	v_cmp_gt_u32_e64 s[98:99], s85, v210
	v_add_f32_e32 v190, v55, v190
	v_cndmask_b32_e64 v54, v208, v190, s[100:101]
	v_add_u32_e32 v211, -15, v154
	v_cmp_gt_u32_e64 s[100:101], s85, v211
	v_add_f32_e32 v191, v39, v191
	v_cndmask_b32_e32 v38, v208, v191, vcc
	v_subrev_u32_e32 v209, 46, v154
	v_cmp_gt_u32_e32 vcc, s85, v209
	v_add_f32_e32 v192, v56, v192
	v_cndmask_b32_e64 v55, v208, v192, s[98:99]
	v_add_u32_e32 v210, -14, v154
	v_cmp_gt_u32_e64 s[98:99], s85, v210
	v_add_f32_e32 v193, v40, v193
	v_cndmask_b32_e64 v39, v208, v193, s[100:101]
	v_subrev_u32_e32 v211, 45, v154
	v_cmp_gt_u32_e64 s[100:101], s85, v211
	v_add_f32_e32 v194, v57, v194
	v_cndmask_b32_e32 v56, v208, v194, vcc
	v_add_u32_e32 v209, -13, v154
	v_cmp_gt_u32_e32 vcc, s85, v209
	v_add_f32_e32 v195, v41, v195
	v_cndmask_b32_e64 v40, v208, v195, s[98:99]
	v_subrev_u32_e32 v210, 44, v154
	v_cmp_gt_u32_e64 s[98:99], s85, v210
	v_add_f32_e32 v196, v58, v196
	v_cndmask_b32_e64 v57, v208, v196, s[100:101]
	v_add_u32_e32 v211, -12, v154
	v_cmp_gt_u32_e64 s[100:101], s85, v211
	v_add_f32_e32 v197, v42, v197
	v_cndmask_b32_e32 v41, v208, v197, vcc
	v_subrev_u32_e32 v209, 39, v154
	v_cmp_gt_u32_e32 vcc, s85, v209
	v_add_f32_e32 v198, v59, v198
	v_cndmask_b32_e64 v155, v208, v198, s[98:99]
	v_add_u32_e32 v210, -7, v154
	v_cmp_gt_u32_e64 s[98:99], s85, v210
	v_add_f32_e32 v199, v43, v199
	v_cndmask_b32_e64 v58, v208, v199, s[100:101]
	v_subrev_u32_e32 v211, 38, v154
	v_cmp_gt_u32_e64 s[100:101], s85, v211
	v_add_f32_e32 v200, v60, v200
	v_cndmask_b32_e32 v156, v208, v200, vcc
	v_add_u32_e32 v209, -6, v154
	v_cmp_gt_u32_e32 vcc, s85, v209
	v_add_f32_e32 v201, v44, v201
	v_cndmask_b32_e64 v59, v208, v201, s[98:99]
	v_subrev_u32_e32 v210, 37, v154
	v_cmp_gt_u32_e64 s[98:99], s85, v210
	v_add_f32_e32 v202, v61, v202
	v_cndmask_b32_e64 v158, v208, v202, s[100:101]
	v_add_u32_e32 v211, -5, v154
	v_cmp_gt_u32_e64 s[100:101], s85, v211
	v_add_f32_e32 v203, v45, v203
	v_cndmask_b32_e32 v157, v208, v203, vcc
	s_waitcnt lgkmcnt(0)
; #define LDS_WAIT() asm volatile("s_waitcnt lgkmcnt(0)" ::: "memory")
; __device__ __forceinline__ int crow(int r, int hi) { return (r & 3) + 8 * (r >> 2) + 4 * hi; }
; template <int MODE>
; __device__ __forceinline__ void attn_unit(const Params& P, unsigned char* lds, int h, int rb, int grp, bool dry = false) {
;     ...
;                     p0[r] = ((unsigned)(base + c0 + 128) <= 256u) ? p0[r] + tb[c0] : -1e30f;
;                     p1[r] = ((unsigned)(base + c0 + 32 + 128) <= 256u) ? p1[r] + tb[c0 + 32] : -1e30f; } }
;             float pmax = p0[0];
; #pragma unroll
;             for (int r = 1; r < 16; ++r) pmax = fmaxf(pmax, p0[r]);
; #pragma unroll
;             for (int r = 0; r < 16; ++r) pmax = fmaxf(pmax, p1[r]);
;             { auto rr = __builtin_amdgcn_permlane32_swap(__float_as_uint(pmax), __float_as_uint(pmax), false, false); pmax = fmaxf(__uint_as_float(rr[0]), __uint_as_float(rr[1])); }
;             const float mn = fmaxf(m_reg, pmax); const float alpha = __builtin_amdgcn_exp2f(m_reg - mn); m_reg = mn;
; #pragma unroll
;             for (int r = 0; r < 16; ++r) { p0[r] = __builtin_amdgcn_exp2f(p0[r] - mn); p1[r] = __builtin_amdgcn_exp2f(p1[r] - mn); }
;             float ps = 0.f;
; #pragma unroll
;             for (int r = 0; r < 16; ++r) ps += p0[r] + p1[r];
;             { auto rr = __builtin_amdgcn_permlane32_swap(__float_as_uint(ps), __float_as_uint(ps), false, false); ps = __uint_as_float(rr[0]) + __uint_as_float(rr[1]); }
;             l_reg = l_reg * alpha + ps;
;             if (__any(alpha < 1.f)) { if (hi == 0) al_l[r32] = alpha; LDS_WAIT();
; #pragma unroll
;                 for (int d = 0; d < 2; ++d)
; #pragma unroll
;                     for (int r = 0; r < 16; ++r) o[d][r] *= al_l[crow(r, hi)];
;                 LDS_WAIT(); }
	v_subrev_u32_e32 v209, 36, v154
	v_cmp_gt_u32_e32 vcc, s85, v209
	v_add_f32_e32 v204, v62, v204
	v_cndmask_b32_e64 v160, v208, v204, s[98:99]
	v_add_u32_e32 v210, -4, v154
	v_cmp_gt_u32_e64 s[98:99], s85, v210
	v_add_f32_e32 v205, v46, v205
	v_cndmask_b32_e64 v159, v208, v205, s[100:101]
	v_add_f32_e32 v206, v63, v206
	v_cndmask_b32_e32 v162, v208, v206, vcc
	v_add_f32_e32 v207, v47, v207
	v_cndmask_b32_e64 v161, v208, v207, s[98:99]
	v_max_f32_e32 v32, v153, v153
	v_max_f32_e32 v42, v152, v152
	v_max_f32_e32 v32, v42, v32
	v_max3_f32 v32, v32, v49, v50
	v_max3_f32 v32, v32, v51, v52
	v_max3_f32 v32, v32, v53, v54
	v_max3_f32 v32, v32, v55, v56
	v_max3_f32 v32, v32, v57, v155
	v_max3_f32 v32, v32, v156, v158
	v_max3_f32 v32, v32, v160, v162
	v_max3_f32 v32, v32, v151, v48
	v_max3_f32 v32, v32, v33, v34
	v_max3_f32 v32, v32, v35, v36
	v_max3_f32 v32, v32, v37, v38
	v_max3_f32 v32, v32, v39, v40
	v_max3_f32 v32, v32, v41, v58
	v_max3_f32 v32, v32, v59, v157
	v_max3_f32 v32, v32, v159, v161
	v_mov_b32_e32 v42, v32
	s_nop 1
	v_permlane32_swap_b32_e32 v32, v42
	v_max3_f32 v32, v150, v32, v42
	v_sub_f32_e32 v42, v152, v32
	v_sub_f32_e32 v44, v49, v32
	v_exp_f32_e32 v60, v42
	v_sub_f32_e32 v42, v151, v32
	v_sub_f32_e32 v43, v153, v32
	v_exp_f32_e32 v49, v44
	v_sub_f32_e32 v44, v50, v32
	v_exp_f32_e32 v42, v42
	v_exp_f32_e32 v61, v43
	v_sub_f32_e32 v43, v48, v32
	v_exp_f32_e32 v50, v44
	v_sub_f32_e32 v44, v51, v32
	v_exp_f32_e32 v43, v43
	v_sub_f32_e32 v33, v33, v32
	v_exp_f32_e32 v51, v44
	v_sub_f32_e32 v44, v52, v32
	v_sub_f32_e32 v36, v36, v32
	v_exp_f32_e32 v33, v33
	v_sub_f32_e32 v34, v34, v32
	v_exp_f32_e32 v62, v44
	v_exp_f32_e32 v44, v36
	v_sub_f32_e32 v36, v53, v32
	v_exp_f32_e32 v34, v34
	v_sub_f32_e32 v35, v35, v32
	v_exp_f32_e32 v63, v36
	v_sub_f32_e32 v36, v37, v32
	v_exp_f32_e32 v35, v35
	v_exp_f32_e32 v45, v36
	v_sub_f32_e32 v36, v54, v32
	v_add_f32_e32 v151, v60, v42
	v_sub_f32_e32 v154, v150, v32
	v_exp_f32_e32 v150, v36
	v_sub_f32_e32 v36, v38, v32
	v_add_f32_e32 v151, 0, v151
	v_add_f32_e32 v152, v61, v43
	v_exp_f32_e32 v46, v36
	v_sub_f32_e32 v36, v55, v32
	v_add_f32_e32 v151, v152, v151
	v_add_f32_e32 v152, v49, v33
	v_exp_f32_e32 v52, v36
	v_sub_f32_e32 v36, v39, v32
	v_sub_f32_e32 v37, v56, v32
	v_add_f32_e32 v151, v152, v151
	v_add_f32_e32 v152, v50, v34
	v_exp_f32_e32 v36, v36
	v_exp_f32_e32 v53, v37
	v_sub_f32_e32 v37, v40, v32
	v_sub_f32_e32 v38, v57, v32
	v_add_f32_e32 v151, v152, v151
	v_add_f32_e32 v152, v51, v35
	v_exp_f32_e32 v37, v37
	v_exp_f32_e32 v54, v38
	v_sub_f32_e32 v38, v41, v32
	v_sub_f32_e32 v39, v155, v32
	v_add_f32_e32 v151, v152, v151
	v_add_f32_e32 v152, v62, v44
	v_exp_f32_e32 v38, v38
	v_exp_f32_e32 v55, v39
	v_sub_f32_e32 v39, v58, v32
	v_sub_f32_e32 v40, v156, v32
	v_add_f32_e32 v151, v152, v151
	v_add_f32_e32 v152, v63, v45
	v_exp_f32_e32 v39, v39
	v_exp_f32_e32 v56, v40
	v_sub_f32_e32 v40, v59, v32
	v_sub_f32_e32 v41, v158, v32
	v_add_f32_e32 v151, v152, v151
	v_add_f32_e32 v152, v150, v46
	v_exp_f32_e32 v40, v40
	v_exp_f32_e32 v57, v41
	v_sub_f32_e32 v41, v157, v32
	v_sub_f32_e32 v47, v160, v32
	v_add_f32_e32 v151, v152, v151
	v_add_f32_e32 v152, v52, v36
	v_exp_f32_e32 v41, v41
	v_exp_f32_e32 v58, v47
	v_sub_f32_e32 v47, v159, v32
	v_sub_f32_e32 v48, v162, v32
	v_add_f32_e32 v151, v152, v151
	v_add_f32_e32 v152, v53, v37
	v_exp_f32_e32 v47, v47
	v_exp_f32_e32 v59, v48
	v_sub_f32_e32 v48, v161, v32
	v_add_f32_e32 v151, v152, v151
	v_add_f32_e32 v152, v54, v38
	v_exp_f32_e32 v48, v48
	v_add_f32_e32 v151, v152, v151
	v_add_f32_e32 v152, v55, v39
	v_add_f32_e32 v151, v152, v151
	v_add_f32_e32 v152, v56, v40
	v_add_f32_e32 v151, v152, v151
	v_add_f32_e32 v152, v57, v41
	v_add_f32_e32 v151, v152, v151
	v_add_f32_e32 v152, v58, v47
	v_add_f32_e32 v151, v152, v151
	v_add_f32_e32 v152, v59, v48
	v_add_f32_e32 v152, v152, v151
	v_exp_f32_e32 v151, v154
	v_mov_b32_e32 v153, v152
	s_nop 1
	v_permlane32_swap_b32_e32 v152, v153
	v_cmp_gt_f32_e32 vcc, 1.0, v151
	s_cbranch_vccz .LBB0_312
	s_and_saveexec_b64 s[16:17], s[4:5]
	ds_write_b32 v142, v151 offset:43136
	s_or_b64 exec, exec, s[16:17]
	s_waitcnt lgkmcnt(0)
	ds_read_b128 v[154:157], v145 offset:43232
	ds_read_b128 v[158:161], v145 offset:43200
	ds_read_b128 v[162:165], v145 offset:43168
	ds_read_b128 v[166:169], v145 offset:43136
	s_waitcnt lgkmcnt(0)
	s_waitcnt lgkmcnt(3)
	v_pk_mul_f32 v[14:15], v[14:15], v[156:157]
	s_waitcnt lgkmcnt(2)
	v_pk_mul_f32 v[10:11], v[10:11], v[160:161]
	s_waitcnt lgkmcnt(1)
	v_pk_mul_f32 v[6:7], v[6:7], v[164:165]
	s_waitcnt lgkmcnt(0)
	v_pk_mul_f32 v[2:3], v[2:3], v[168:169]
	v_pk_mul_f32 v[30:31], v[30:31], v[156:157]
	v_pk_mul_f32 v[26:27], v[26:27], v[160:161]
	v_pk_mul_f32 v[22:23], v[22:23], v[164:165]
	v_pk_mul_f32 v[18:19], v[18:19], v[168:169]
	v_pk_mul_f32 v[12:13], v[12:13], v[154:155]
	v_pk_mul_f32 v[8:9], v[8:9], v[158:159]
	v_pk_mul_f32 v[4:5], v[4:5], v[162:163]
	v_pk_mul_f32 v[0:1], v[0:1], v[166:167]
	v_pk_mul_f32 v[28:29], v[28:29], v[154:155]
	v_pk_mul_f32 v[24:25], v[24:25], v[158:159]
	v_pk_mul_f32 v[20:21], v[20:21], v[162:163]
	v_pk_mul_f32 v[16:17], v[16:17], v[166:167]

; template <int MODE>
; __device__ __forceinline__ void attn_unit(const Params& P, unsigned char* lds, int h, int rb, int grp, bool dry = false) {
;     ...
;             f32x16 p0 = {}, p1 = {};
;             const unsigned char* Kb = lds + A_K0 + buf * A_KBUF;
; #pragma unroll
;             for (int d0 = 0; d0 < ND; ++d0) { const int cb = (d0 * 16 + hi * 8) * 2;
;                 const bf16x8 b0 = *(const bf16x8*)(Kb + r32 * KSTR + cb), b1 = *(const bf16x8*)(Kb + (32 + r32) * KSTR + cb);
;                 p0 = __builtin_amdgcn_mfma_f32_32x32x16_bf16(b0, qr[d0], p0, 0, 0, 0);
;                 p1 = __builtin_amdgcn_mfma_f32_32x32x16_bf16(b1, qr[d0], p1, 0, 0, 0); }
;             if (MODE == 0) { const int dr = na_tlo + j - na_r; const float* tb = tab + (dr + 7) * 128 + (4 * hi - na_cq + 63); const int v = 4 * hi - na_cs;
; #pragma unroll
;                 for (int r = 0; r < 16; ++r) { const int c0 = (r & 3) + 8 * (r >> 2);
;                     p0[r] = ((unsigned)(c0 + v) < 16u) ? p0[r] + tb[c0] : -1e30f;
;                     p1[r] = ((unsigned)(c0 + 32 + v) < 16u) ? p1[r] + tb[c0 + 32] : -1e30f; } }
.LBB0_330:
	s_add_i32 s82, s93, s97
	s_cmp_ge_u32 s82, s94
	s_cselect_b64 s[80:81], -1, 0
	s_cmp_lt_u32 s82, s95
	s_cselect_b64 vcc, -1, 0
	s_and_b64 s[80:81], s[80:81], vcc
	s_andn2_b64 vcc, exec, s[80:81]
	s_cbranch_vccnz .LBB0_400
	s_and_b32 s82, s97, 1
	s_mul_i32 s80, s82, 0x3400
	v_add_u32_e32 v153, s80, v148
	ds_read_b32 v176, v149
	ds_read_b32 v177, v149 offset:128
	ds_read_b32 v178, v149 offset:4
	ds_read_b32 v179, v149 offset:132
	ds_read_b32 v180, v149 offset:8
	ds_read_b32 v181, v149 offset:136
	ds_read_b32 v182, v149 offset:12
	ds_read_b32 v183, v149 offset:140
	ds_read_b32 v184, v149 offset:32
	ds_read_b32 v185, v149 offset:160
	ds_read_b32 v186, v149 offset:36
	ds_read_b32 v187, v149 offset:164
	ds_read_b32 v188, v149 offset:40
	ds_read_b32 v189, v149 offset:168
	ds_read_b128 v[32:35], v153
	ds_read_b128 v[154:157], v153 offset:32
	s_waitcnt lgkmcnt(1)
	v_mfma_f32_32x32x16_bf16 v[48:63], v[32:35], v[64:67], 0
	ds_read_b128 v[32:35], v153 offset:6656
	s_waitcnt lgkmcnt(1)
	v_mfma_f32_32x32x16_bf16 v[48:63], v[154:157], v[68:71], v[48:63]
	ds_read_b128 v[154:157], v153 offset:6688
	s_waitcnt lgkmcnt(1)
	v_mfma_f32_32x32x16_bf16 v[32:47], v[32:35], v[64:67], 0
	s_waitcnt lgkmcnt(0)
	v_mfma_f32_32x32x16_bf16 v[32:47], v[154:157], v[68:71], v[32:47]
	ds_read_b128 v[154:157], v153 offset:64
	s_waitcnt lgkmcnt(0)
	v_mfma_f32_32x32x16_bf16 v[48:63], v[154:157], v[72:75], v[48:63]
	ds_read_b128 v[154:157], v153 offset:6720
	s_waitcnt lgkmcnt(0)
	v_mfma_f32_32x32x16_bf16 v[32:47], v[154:157], v[72:75], v[32:47]
	ds_read_b128 v[154:157], v153 offset:96
	s_waitcnt lgkmcnt(0)
	v_mfma_f32_32x32x16_bf16 v[48:63], v[154:157], v[76:79], v[48:63]
	ds_read_b128 v[156:159], v153 offset:6752
	s_waitcnt lgkmcnt(0)
	v_mfma_f32_32x32x16_bf16 v[32:47], v[156:159], v[76:79], v[32:47]
	v_mov_b32_e32 v208, 0xf149f2ca
	ds_read_b32 v190, v149 offset:44
	ds_read_b32 v191, v149 offset:172
	ds_read_b32 v192, v149 offset:64
	ds_read_b32 v193, v149 offset:192
	ds_read_b32 v194, v149 offset:68
	ds_read_b32 v195, v149 offset:196
	ds_read_b32 v196, v149 offset:72
	ds_read_b32 v197, v149 offset:200
	ds_read_b32 v198, v149 offset:76
	ds_read_b32 v199, v149 offset:204
	ds_read_b32 v200, v149 offset:96
	ds_read_b32 v201, v149 offset:224
	ds_read_b32 v202, v149 offset:100
	ds_read_b32 v203, v149 offset:228
	v_add_f32_e32 v176, v48, v176
	v_cndmask_b32_e64 v154, v208, v176, s[6:7]
	v_add_f32_e32 v177, v32, v177
	v_cndmask_b32_e64 v153, v208, v177, s[8:9]
	v_add_f32_e32 v178, v49, v178
	v_cndmask_b32_e64 v155, v208, v178, s[10:11]
	v_add_f32_e32 v179, v33, v179
	v_cndmask_b32_e64 v48, v208, v179, s[12:13]
	v_add_f32_e32 v180, v50, v180
	v_cndmask_b32_e64 v49, v208, v180, s[14:15]
	v_add_f32_e32 v181, v34, v181
	v_cndmask_b32_e64 v33, v208, v181, s[16:17]
	v_add_f32_e32 v182, v51, v182
	v_cndmask_b32_e64 v50, v208, v182, s[18:19]
	v_add_f32_e32 v183, v35, v183
	v_cndmask_b32_e64 v34, v208, v183, s[20:21]
	v_add_f32_e32 v184, v52, v184
	v_cndmask_b32_e64 v51, v208, v184, s[22:23]
	v_add_f32_e32 v185, v36, v185
	v_cndmask_b32_e64 v35, v208, v185, s[24:25]
	v_add_f32_e32 v186, v53, v186
	v_cndmask_b32_e64 v52, v208, v186, s[26:27]
	v_add_f32_e32 v187, v37, v187
	v_cndmask_b32_e64 v36, v208, v187, s[28:29]
	v_add_f32_e32 v188, v54, v188
	v_cndmask_b32_e64 v53, v208, v188, s[30:31]
	v_add_f32_e32 v189, v38, v189
	v_cndmask_b32_e64 v37, v208, v189, s[34:35]
	s_waitcnt lgkmcnt(0)
	ds_read_b32 v204, v149 offset:104
	ds_read_b32 v205, v149 offset:232
	ds_read_b32 v206, v149 offset:108
	ds_read_b32 v207, v149 offset:236
	v_add_f32_e32 v190, v55, v190
	v_cndmask_b32_e64 v54, v208, v190, s[36:37]
	v_add_f32_e32 v191, v39, v191
	v_cndmask_b32_e64 v38, v208, v191, s[38:39]
	v_add_f32_e32 v192, v56, v192
	v_cndmask_b32_e64 v55, v208, v192, s[40:41]
	v_add_f32_e32 v193, v40, v193
	v_cndmask_b32_e64 v39, v208, v193, s[42:43]
	v_add_f32_e32 v194, v57, v194
	v_cndmask_b32_e64 v56, v208, v194, s[44:45]
	v_add_f32_e32 v195, v41, v195
	v_cndmask_b32_e64 v40, v208, v195, s[46:47]
	v_add_f32_e32 v196, v58, v196
	v_cndmask_b32_e64 v156, v208, v196, s[48:49]
	v_add_f32_e32 v197, v42, v197
	v_cndmask_b32_e64 v57, v208, v197, s[50:51]
	v_add_f32_e32 v198, v59, v198
	v_cndmask_b32_e64 v157, v208, v198, s[52:53]
	v_add_f32_e32 v199, v43, v199
	v_cndmask_b32_e64 v58, v208, v199, s[54:55]
	v_add_f32_e32 v200, v60, v200
	v_cndmask_b32_e64 v159, v208, v200, s[56:57]
	v_add_f32_e32 v201, v44, v201
	v_cndmask_b32_e64 v158, v208, v201, s[58:59]
	v_add_f32_e32 v202, v61, v202
	v_cndmask_b32_e64 v161, v208, v202, s[60:61]
	v_add_f32_e32 v203, v45, v203
	v_cndmask_b32_e64 v160, v208, v203, s[62:63]
	s_waitcnt lgkmcnt(0)
; #define LDS_WAIT() asm volatile("s_waitcnt lgkmcnt(0)" ::: "memory")
; __device__ __forceinline__ int crow(int r, int hi) { return (r & 3) + 8 * (r >> 2) + 4 * hi; }
; template <int MODE>
; __device__ __forceinline__ void attn_unit(const Params& P, unsigned char* lds, int h, int rb, int grp, bool dry = false) {
;     ...
;                     p0[r] = ((unsigned)(c0 + v) < 16u) ? p0[r] + tb[c0] : -1e30f;
;                     p1[r] = ((unsigned)(c0 + 32 + v) < 16u) ? p1[r] + tb[c0 + 32] : -1e30f; } }
;             if (MODE == 1) { const int base = key0 + 64 * j - t0 + 4 * hi - 32 * wid - r32; const float* tb = tab + 512 + base;
; #pragma unroll
;                 for (int r = 0; r < 16; ++r) { const int c0 = (r & 3) + 8 * (r >> 2);
;                     p0[r] = ((unsigned)(base + c0 + 128) <= 256u) ? p0[r] + tb[c0] : -1e30f;
;                     p1[r] = ((unsigned)(base + c0 + 32 + 128) <= 256u) ? p1[r] + tb[c0 + 32] : -1e30f; } }
;             float pmax = p0[0];
; #pragma unroll
;             for (int r = 1; r < 16; ++r) pmax = fmaxf(pmax, p0[r]);
; #pragma unroll
;             for (int r = 0; r < 16; ++r) pmax = fmaxf(pmax, p1[r]);
;             { auto rr = __builtin_amdgcn_permlane32_swap(__float_as_uint(pmax), __float_as_uint(pmax), false, false); pmax = fmaxf(__uint_as_float(rr[0]), __uint_as_float(rr[1])); }
;             const float mn = fmaxf(m_reg, pmax); const float alpha = __builtin_amdgcn_exp2f(m_reg - mn); m_reg = mn;
; #pragma unroll
;             for (int r = 0; r < 16; ++r) { p0[r] = __builtin_amdgcn_exp2f(p0[r] - mn); p1[r] = __builtin_amdgcn_exp2f(p1[r] - mn); }
;             float ps = 0.f;
; #pragma unroll
;             for (int r = 0; r < 16; ++r) ps += p0[r] + p1[r];
;             { auto rr = __builtin_amdgcn_permlane32_swap(__float_as_uint(ps), __float_as_uint(ps), false, false); ps = __uint_as_float(rr[0]) + __uint_as_float(rr[1]); }
;             l_reg = l_reg * alpha + ps;
;             if (__any(alpha < 1.f)) { if (hi == 0) al_l[r32] = alpha; LDS_WAIT();
; #pragma unroll
;                 for (int d = 0; d < 2; ++d)
; #pragma unroll
;                     for (int r = 0; r < 16; ++r) o[d][r] *= al_l[crow(r, hi)];
;                 LDS_WAIT(); }
	v_add_f32_e32 v204, v62, v204
	v_cndmask_b32_e64 v163, v208, v204, s[64:65]
	v_add_f32_e32 v205, v46, v205
	v_cndmask_b32_e64 v162, v208, v205, s[66:67]
	v_add_f32_e32 v206, v63, v206
	v_cndmask_b32_e64 v165, v208, v206, s[68:69]
	v_add_f32_e32 v207, v47, v207
	v_cndmask_b32_e64 v164, v208, v207, s[70:71]
	v_max_f32_e32 v32, v155, v155
	v_max_f32_e32 v41, v154, v154
	v_max_f32_e32 v32, v41, v32
	v_max3_f32 v32, v32, v49, v50
	v_max3_f32 v32, v32, v51, v52
	v_max3_f32 v32, v32, v53, v54
	v_max3_f32 v32, v32, v55, v56
	v_max3_f32 v32, v32, v156, v157
	v_max3_f32 v32, v32, v159, v161
	v_max3_f32 v32, v32, v163, v165
	v_max3_f32 v32, v32, v153, v48
	v_max3_f32 v32, v32, v33, v34
	v_max3_f32 v32, v32, v35, v36
	v_max3_f32 v32, v32, v37, v38
	v_max3_f32 v32, v32, v39, v40
	v_max3_f32 v32, v32, v57, v58
	v_max3_f32 v32, v32, v158, v160
	v_max3_f32 v32, v32, v162, v164
	v_mov_b32_e32 v41, v32
	s_nop 1
	v_permlane32_swap_b32_e32 v32, v41
	v_max3_f32 v32, v152, v32, v41
	v_sub_f32_e32 v41, v154, v32
	v_sub_f32_e32 v43, v49, v32
	v_exp_f32_e32 v59, v41
	v_sub_f32_e32 v41, v153, v32
	v_sub_f32_e32 v42, v155, v32
	v_exp_f32_e32 v49, v43
	v_sub_f32_e32 v43, v50, v32
	v_exp_f32_e32 v41, v41
	v_exp_f32_e32 v60, v42
	v_sub_f32_e32 v42, v48, v32
	v_exp_f32_e32 v50, v43
	v_sub_f32_e32 v43, v51, v32
	v_exp_f32_e32 v42, v42
	v_sub_f32_e32 v33, v33, v32
	v_exp_f32_e32 v51, v43
	v_sub_f32_e32 v43, v52, v32
	v_sub_f32_e32 v36, v36, v32
	v_exp_f32_e32 v33, v33
	v_sub_f32_e32 v34, v34, v32
	v_exp_f32_e32 v61, v43
	v_exp_f32_e32 v43, v36
	v_sub_f32_e32 v36, v53, v32
	v_exp_f32_e32 v34, v34
	v_sub_f32_e32 v35, v35, v32
	v_exp_f32_e32 v62, v36
	v_sub_f32_e32 v36, v37, v32
	v_exp_f32_e32 v35, v35
	v_exp_f32_e32 v44, v36
	v_sub_f32_e32 v36, v54, v32
	v_add_f32_e32 v153, v59, v41
	v_exp_f32_e32 v63, v36
	v_sub_f32_e32 v36, v38, v32
	v_add_f32_e32 v153, 0, v153
	v_add_f32_e32 v154, v60, v42
	v_exp_f32_e32 v45, v36
	v_sub_f32_e32 v36, v55, v32
	v_add_f32_e32 v153, v154, v153
	v_add_f32_e32 v154, v49, v33
	v_exp_f32_e32 v52, v36
	v_sub_f32_e32 v36, v39, v32
	v_sub_f32_e32 v37, v56, v32
	v_add_f32_e32 v153, v154, v153
	v_add_f32_e32 v154, v50, v34
	v_exp_f32_e32 v36, v36
	v_exp_f32_e32 v53, v37
	v_sub_f32_e32 v37, v40, v32
	v_sub_f32_e32 v38, v156, v32
	v_add_f32_e32 v153, v154, v153
	v_add_f32_e32 v154, v51, v35
	v_exp_f32_e32 v37, v37
	v_exp_f32_e32 v54, v38
	v_sub_f32_e32 v38, v57, v32
	v_sub_f32_e32 v39, v157, v32
	v_add_f32_e32 v153, v154, v153
	v_add_f32_e32 v154, v61, v43
	v_exp_f32_e32 v38, v38
	v_exp_f32_e32 v55, v39
	v_sub_f32_e32 v39, v58, v32
	v_sub_f32_e32 v40, v159, v32
	v_add_f32_e32 v153, v154, v153
	v_add_f32_e32 v154, v62, v44
	v_exp_f32_e32 v39, v39
	v_exp_f32_e32 v56, v40
	v_sub_f32_e32 v40, v158, v32
	v_sub_f32_e32 v46, v161, v32
	v_add_f32_e32 v153, v154, v153
	v_add_f32_e32 v154, v63, v45
	v_exp_f32_e32 v40, v40
	v_exp_f32_e32 v57, v46
	v_sub_f32_e32 v46, v160, v32
	v_sub_f32_e32 v47, v163, v32
	v_add_f32_e32 v153, v154, v153
	v_add_f32_e32 v154, v52, v36
	v_exp_f32_e32 v46, v46
	v_exp_f32_e32 v58, v47
	v_sub_f32_e32 v47, v162, v32
	v_sub_f32_e32 v48, v165, v32
	v_add_f32_e32 v153, v154, v153
	v_add_f32_e32 v154, v53, v37
	v_sub_f32_e32 v166, v152, v32
	v_exp_f32_e32 v47, v47
	v_exp_f32_e32 v152, v48
	v_sub_f32_e32 v48, v164, v32
	v_add_f32_e32 v153, v154, v153
	v_add_f32_e32 v154, v54, v38
	v_exp_f32_e32 v48, v48
	v_add_f32_e32 v153, v154, v153
	v_add_f32_e32 v154, v55, v39
	v_add_f32_e32 v153, v154, v153
	v_add_f32_e32 v154, v56, v40
	v_add_f32_e32 v153, v154, v153
	v_add_f32_e32 v154, v57, v46
	v_add_f32_e32 v153, v154, v153
	v_add_f32_e32 v154, v58, v47
	v_add_f32_e32 v153, v154, v153
	v_add_f32_e32 v154, v152, v48
	v_add_f32_e32 v154, v154, v153
	v_exp_f32_e32 v153, v166
	v_mov_b32_e32 v155, v154
	s_nop 1
	v_permlane32_swap_b32_e32 v154, v155
	v_cmp_gt_f32_e32 vcc, 1.0, v153
	s_cbranch_vccz .LBB0_399
	s_and_saveexec_b64 s[80:81], s[4:5]
	ds_write_b32 v144, v153 offset:43136
	s_or_b64 exec, exec, s[80:81]
	s_waitcnt lgkmcnt(0)
	ds_read_b128 v[156:159], v88 offset:43232
	ds_read_b128 v[160:163], v88 offset:43200
	ds_read_b128 v[164:167], v88 offset:43168
	ds_read_b128 v[172:175], v88 offset:43136
	s_waitcnt lgkmcnt(0)
	s_waitcnt lgkmcnt(3)
	v_pk_mul_f32 v[14:15], v[14:15], v[158:159]
	s_waitcnt lgkmcnt(2)
	v_pk_mul_f32 v[10:11], v[10:11], v[162:163]
	s_waitcnt lgkmcnt(1)
	v_pk_mul_f32 v[6:7], v[6:7], v[166:167]
	s_waitcnt lgkmcnt(0)
	v_pk_mul_f32 v[2:3], v[2:3], v[174:175]
	v_pk_mul_f32 v[30:31], v[30:31], v[158:159]
	v_pk_mul_f32 v[26:27], v[26:27], v[162:163]
	v_pk_mul_f32 v[22:23], v[22:23], v[166:167]
	v_pk_mul_f32 v[18:19], v[18:19], v[174:175]
	v_pk_mul_f32 v[12:13], v[12:13], v[156:157]
	v_pk_mul_f32 v[8:9], v[8:9], v[160:161]
	v_pk_mul_f32 v[4:5], v[4:5], v[164:165]
	v_pk_mul_f32 v[0:1], v[0:1], v[172:173]
	v_pk_mul_f32 v[28:29], v[28:29], v[156:157]
	v_pk_mul_f32 v[24:25], v[24:25], v[160:161]
	v_pk_mul_f32 v[20:21], v[20:21], v[164:165]
	v_pk_mul_f32 v[16:17], v[16:17], v[172:173]

; __device__ __forceinline__ int v_st(int k, int c) { const int kk = (k & ~0xC) | ((k & 4) << 1) | ((k & 8) >> 1); return ((kk >> 3) * 2 + (c >> 5)) * 512 + ((kk & 7) * 32 + (c & 31)) * 2; }
; __device__ __forceinline__ int v_rd_base_kp(int lane) { return ((lane & 3) << 3) | (((lane >> 2) & 3) << 6) | (((lane >> 4) & 1) << 5) | (((lane >> 5) & 1) << 10); }
; __device__ __forceinline__ void mla_unit2(const Params& P, unsigned char* lds, int h, int rb, int grp, bool dry = false) {
;     ...
;     float l_reg = 0.f, alpha = 1.f; f32x16 o[2] = {}; f32x16 p0, p1; bf16x8 pa0, pa1, pa2, pa3; f32x16 negm = {}; bool first = true;
;     const int sr = tid >> 3, sc = (tid & 7) * 8, pr = (tid & 255) >> 2, pc = (tid & 3) * 8;
;     const int vst = v_st(sr, sc);
;     const int vb0 = (int)(uintptr_t)(lds + A_V0) + v_rd_base_kp(lane);
;     const unsigned char* K0 = lds + A_K0; const unsigned char* K1 = lds + A_K0 + A_KBUF;
;     unsigned char* kwE = lds + A_K0 + (hoff ? 0 : A_KBUF); unsigned char* vwE = lds + A_V0 + (hoff ? A_VBUF : 0);
;     unsigned char* kwO = lds + A_K0 + (hoff ? A_KBUF : 0); unsigned char* vwO = lds + A_V0 + (hoff ? 0 : A_VBUF);
;     bf16x8 ksE, vsE, psE, ksO, vsO, psO;
;     const bf16_t* Kth = Kp + (size_t)(seq0 + sr) * 1024 + sc; const bf16_t* Vth = Vp + (size_t)(seq0 + sr) * 1024 + sc; const bf16_t* Pth = Kpe + (size_t)(seq0 + pr) * 32 + pc;
.LBB0_962:
	s_cmp_lg_u32 s41, -1
	v_add_f32_e32 v36, v93, v158
	s_cselect_b32 s4, s41, 0
	v_add_f32_e32 v36, 0, v36
	v_add_f32_e32 v203, v34, v35
	s_addk_i32 s4, 0x2000
	v_fmac_f32_e32 v203, v36, v33
	v_add_u32_e32 v204, s4, v159
	s_setprio 0
	s_ashr_i32 s41, s40, 31
	s_lshl_b64 s[4:5], s[40:41], 17
	v_lshl_add_u64 v[34:35], s[4:5], 0, v[94:95]
	s_lshl_b64 s[4:5], s[40:41], 12
	v_and_b32_e32 v33, 7, v160
	s_add_u32 s4, s52, s4
	s_waitcnt lgkmcnt(0)
	s_barrier
	v_lshl_or_b32 v34, v33, 4, v34
	s_addc_u32 s5, 0, s5
	v_mov_b32_e32 v93, v145
	v_and_b32_e32 v33, 3, v160
	v_lshl_add_u64 v[158:159], s[42:43], 1, v[34:35]
	v_lshl_add_u64 v[34:35], s[4:5], 0, v[92:93]
	v_lshlrev_b32_e32 v144, 4, v33
	v_lshl_add_u64 v[160:161], v[34:35], 0, v[144:145]
	s_mov_b32 s41, 2
	s_nop 0
	v_readfirstlane_b32 s60, v158
	v_readfirstlane_b32 s61, v159
	v_readfirstlane_b32 s64, v160
	v_readfirstlane_b32 s65, v161
	v_subrev_u32_e32 v166, s60, v158
	v_subrev_u32_e32 v167, s64, v160
	s_add_u32 s60, s60, s36
	s_addc_u32 s61, s61, s37
	s_add_u32 s64, s64, s36
	s_addc_u32 s65, s65, s37
	s_add_u32 s62, s60, 0x18060000
	s_addc_u32 s63, s61, 0
	s_add_u32 s60, s60, 0x14080000
	s_addc_u32 s61, s61, 0
	s_add_u32 s64, s64, 0x304000
	s_addc_u32 s65, s65, 0
	v_mov_b32_e32 v33, v32
	v_mov_b32_e32 v34, v32
	v_mov_b32_e32 v35, v32
	v_mov_b32_e32 v36, v32
	v_mov_b32_e32 v37, v32
	v_mov_b32_e32 v38, v32
	v_mov_b32_e32 v39, v32
	v_mov_b32_e32 v40, v32
	v_mov_b32_e32 v41, v32
	v_mov_b32_e32 v42, v32
	v_mov_b32_e32 v43, v32
	v_mov_b32_e32 v44, v32
	v_mov_b32_e32 v45, v32
	v_mov_b32_e32 v46, v32
	v_mov_b32_e32 v47, v32
	s_branch .LBB0_965

; #define SLOAD(j) do { const size_t krow = (size_t)(seq0 + key0 + 64 * (j) + sr); kst = *(const bf16x8*)(Kp + krow * ldk + sc); vstg = *(const bf16x8*)(Vp + krow * ldk + sc); \
;         if (MODE == 2) { if (tid < 256) pst = *(const bf16x8*)(Kpe + (size_t)(seq0 + key0 + 64 * (j) + pr) * 32 + pc); } } while (0)
; #define SWRITE(b) do { *(bf16x8*)(lds + A_K0 + (b) * A_KBUF + sr * KSTR + sc * 2) = kst; *(bf16x8*)(lds + A_V0 + (b) * A_VBUF + vst) = vstg; \
;         if (MODE == 2) { if (tid < 256) *(bf16x8*)(lds + A_K0 + (b) * A_KBUF + pr * KSTR + 128 + pc * 2) = pst; } } while (0)
; #define SLOAD(S, j) do { const size_t krow = (size_t)(seq0 + 64 * (j) + sr); ks##S = *(const bf16x8*)(Kp + krow * 1024 + sc); vs##S = *(const bf16x8*)(Vp + krow * 1024 + sc); \
;         ps##S = *(const bf16x8*)(Kpe + (size_t)(seq0 + 64 * (j) + pr) * 32 + pc); } while (0)
; #define SWRITE(b, S) do { *(bf16x8*)(lds + A_K0 + (b) * A_KBUF + sr * KSTR + sc * 2) = ks##S; *(bf16x8*)(lds + A_V0 + (b) * A_VBUF + vst) = vs##S; \
;         if (tid < 256) *(bf16x8*)(lds + A_K0 + (b) * A_KBUF + pr * KSTR + 128 + pc * 2) = ps##S; } while (0)
; #define SBAR() __builtin_amdgcn_sched_barrier(0)
; #define SLOAD(S, t) do { const int t_ = (t); if (t_ + 1 < NT) { ks##S = *(const bf16x8*)(Kth + (size_t)(t_ + 1) * 65536); ps##S = *(const bf16x8*)(Pth + (size_t)(t_ + 1) * 2048); } \
;         if (t_ < NT) { vs##S = *(const bf16x8*)(Vth + (size_t)t_ * 65536); } } while (0)
; #define SWRITE(S, t, kw, vw) do { const int t_ = (t); if (t_ + 1 < NT) { *(bf16x8*)((kw) + sr * KSTR + sc * 2) = ks##S; if (tid < 256) *(bf16x8*)((kw) + pr * KSTR + 128 + pc * 2) = ps##S; } \
;         if (t_ < NT) *(bf16x8*)((vw) + vst) = vs##S; } while (0)
; #define HBAR() do { asm volatile("s_waitcnt lgkmcnt(0)" ::: "memory"); __builtin_amdgcn_s_barrier(); asm volatile("" ::: "memory"); } while (0)
; #define SBAR() __builtin_amdgcn_sched_barrier(0)
; __device__ __forceinline__ void mla_unit2(const Params& P, unsigned char* lds, int h, int rb, int grp, bool dry = false) {
;     ...
;         SLOAD(O, i + 1 + hoff); SBAR();
;         mla_qkt_neg(p0, p1, negm, K0, qr, r32, hi);
;         if (i > 0) { pv_both_kp(o[0], o[1], vb0 + A_VBUF, pa0, pa1, pa2, pa3); }
;         HBAR();
;         __builtin_amdgcn_s_setprio(1);
;         SWRITE(E, i + hoff, kwE, vwE); SBAR();
.LBB0_964:
	v_add_f32_e32 v66, v205, v206
	v_fmac_f32_e32 v66, v203, v144
	v_add_f32_e32 v203, v64, v65
	v_fmac_f32_e32 v203, v66, v80
	s_add_i32 s41, s41, 2
	s_setprio 0
	s_waitcnt lgkmcnt(0)
	s_barrier
	s_add_u32 s60, s60, 0x20000
	s_addc_u32 s61, s61, 0
	s_add_u32 s62, s62, 0x20000
	s_addc_u32 s63, s63, 0
	s_add_u32 s64, s64, 0x1000
	s_addc_u32 s65, s65, 0
	s_cmp_lt_u32 s41, s54
	s_cbranch_scc0 .LBB0_997
.LBB0_965:
	s_add_i32 s47, s40, s41
	s_add_i32 s4, s47, 2
	s_cmp_lt_i32 s4, s54
	s_cselect_b64 s[44:45], -1, 0
	s_cmp_ge_i32 s4, s54
	s_cbranch_scc1 .LBB0_967
	global_load_dwordx4 v[136:139], v166, s[60:61]
	global_load_dwordx4 v[140:143], v167, s[64:65]
.LBB0_967:
	s_add_i32 s4, s47, 1
	s_cmp_lt_i32 s4, s54
	s_cselect_b64 s[42:43], -1, 0
	s_cmp_ge_i32 s4, s54
	s_cbranch_scc1 .LBB0_969
	global_load_dwordx4 v[132:135], v166, s[62:63]
.LBB0_969:
	ds_read_b128 v[80:83], v157
	ds_read_b128 v[146:149], v157 offset:32
	ds_read_b128 v[150:153], v157 offset:6656
	ds_read_b128 v[168:171], v157 offset:6688
	s_waitcnt lgkmcnt(3)
	v_mfma_f32_32x32x16_bf16 v[64:79], v[80:83], v[96:99], v[32:47]
	s_waitcnt lgkmcnt(1)
	v_mfma_f32_32x32x16_bf16 v[80:95], v[150:153], v[96:99], v[32:47]
	v_mfma_f32_32x32x16_bf16 v[64:79], v[146:149], v[100:103], v[64:79]
	ds_read_b128 v[146:149], v157 offset:64
	ds_read_b128 v[150:153], v157 offset:96
	s_waitcnt lgkmcnt(2)
	v_mfma_f32_32x32x16_bf16 v[80:95], v[168:171], v[100:103], v[80:95]
	s_waitcnt lgkmcnt(1)
	v_mfma_f32_32x32x16_bf16 v[64:79], v[146:149], v[104:107], v[64:79]
	ds_read_b128 v[146:149], v157 offset:6720
	ds_read_b128 v[168:171], v157 offset:6752
	s_waitcnt lgkmcnt(1)
	v_mfma_f32_32x32x16_bf16 v[80:95], v[146:149], v[104:107], v[80:95]
	v_mfma_f32_32x32x16_bf16 v[64:79], v[150:153], v[108:111], v[64:79]
	ds_read_b128 v[146:149], v157 offset:128
	ds_read_b128 v[150:153], v157 offset:160
	s_waitcnt lgkmcnt(2)
	v_mfma_f32_32x32x16_bf16 v[80:95], v[168:171], v[108:111], v[80:95]
	s_waitcnt lgkmcnt(1)
	v_mfma_f32_32x32x16_bf16 v[64:79], v[146:149], v[112:115], v[64:79]
	ds_read_b128 v[146:149], v157 offset:6784
	ds_read_b128 v[168:171], v157 offset:6816
	ds_read_b64_tr_b16 v[182:183], v204 offset:0
	ds_read_b64_tr_b16 v[184:185], v204 offset:0x100
	s_waitcnt lgkmcnt(1)
	v_mfma_f32_32x32x16_bf16 v[80:95], v[146:149], v[112:115], v[80:95]
	ds_read_b64_tr_b16 v[146:147], v204 offset:0x800
	ds_read_b64_tr_b16 v[148:149], v204 offset:0x900
	ds_read_b64_tr_b16 v[186:187], v204 offset:0x1000
	ds_read_b64_tr_b16 v[188:189], v204 offset:0x1100
	ds_read_b64_tr_b16 v[190:191], v204 offset:0x1800
	ds_read_b64_tr_b16 v[192:193], v204 offset:0x1900
	ds_read_b64_tr_b16 v[206:207], v204 offset:0x200
	ds_read_b64_tr_b16 v[208:209], v204 offset:0x300
	v_mfma_f32_32x32x16_bf16 v[64:79], v[150:153], v[116:119], v[64:79]
	ds_read_b64_tr_b16 v[150:151], v204 offset:0xa00
	ds_read_b64_tr_b16 v[152:153], v204 offset:0xb00
	ds_read_b64_tr_b16 v[210:211], v204 offset:0x1200
	ds_read_b64_tr_b16 v[212:213], v204 offset:0x1300
	ds_read_b64_tr_b16 v[214:215], v204 offset:0x1a00
	ds_read_b64_tr_b16 v[216:217], v204 offset:0x1b00
	s_waitcnt lgkmcnt(8)
	s_waitcnt lgkmcnt(0)
	v_mfma_f32_32x32x16_bf16 v[80:95], v[168:171], v[116:119], v[80:95]
	v_mfma_f32_32x32x16_bf16 v[0:15], v[60:63], v[182:185], v[0:15]
	s_waitcnt lgkmcnt(0)
	v_mfma_f32_32x32x16_bf16 v[0:15], v[56:59], v[146:149], v[0:15]
	v_mfma_f32_32x32x16_bf16 v[0:15], v[52:55], v[186:189], v[0:15]
	v_mfma_f32_32x32x16_bf16 v[0:15], v[48:51], v[190:193], v[0:15]
	v_mfma_f32_32x32x16_bf16 v[16:31], v[60:63], v[206:209], v[16:31]
	s_waitcnt lgkmcnt(0)
	s_barrier
	v_mfma_f32_32x32x16_bf16 v[16:31], v[56:59], v[150:153], v[16:31]
	v_mfma_f32_32x32x16_bf16 v[16:31], v[52:55], v[210:213], v[16:31]
	v_mfma_f32_32x32x16_bf16 v[16:31], v[48:51], v[214:217], v[16:31]
	s_setprio 1
	s_cmp_lg_u64 s[44:45], 0
	s_cbranch_scc0 .Lmla_w1_tail
	s_waitcnt vmcnt(5)
	ds_write_b128 v196, v[120:123]
	s_and_saveexec_b64 s[12:13], s[8:9]
	s_cbranch_execz .Lmla_w1_nope
	v_add_u32_e32 v48, v155, v156
	s_waitcnt vmcnt(4)
	ds_write_b128 v48, v[124:127] offset:128
.Lmla_w1_nope:
	s_or_b64 exec, exec, s[12:13]
	s_waitcnt vmcnt(3)
	ds_write_b128 v197, v[128:131] offset:26624
	s_branch .LBB0_975
.Lmla_w1_tail:
	s_cmp_ge_i32 s47, s55
	s_cbranch_scc1 .LBB0_973
	s_waitcnt vmcnt(1)
	ds_write_b128 v196, v[120:123]
	s_and_saveexec_b64 s[12:13], s[8:9]
	s_cbranch_execz .LBB0_972
	v_add_u32_e32 v48, v155, v156
	s_waitcnt vmcnt(0)
	ds_write_b128 v48, v[124:127] offset:128

; __device__ __forceinline__ void mla_softmax_rel_kp(f32x16& p0, f32x16& p1, f32x16& negm, bool first, float& l_reg, float& alpha, bf16x8& pa0, bf16x8& pa1, bf16x8& pa2, bf16x8& pa3) {
;     float pmax = p0[0];
; #pragma unroll
;     for (int r = 1; r < 16; ++r) pmax = fmaxf(pmax, p0[r]);
; #pragma unroll
;     for (int r = 0; r < 16; ++r) pmax = fmaxf(pmax, p1[r]);
;     { auto rr = __builtin_amdgcn_permlane32_swap(__float_as_uint(pmax), __float_as_uint(pmax), false, false); pmax = fmaxf(__uint_as_float(rr[0]), __uint_as_float(rr[1])); }
;     alpha = 1.f;
;     if (__builtin_expect(first || !__all(pmax <= THR2), 0)) {
;         const float d = first ? pmax : fmaxf(pmax, 0.f);
;         if (!first) alpha = __builtin_amdgcn_exp2f(-d);
;         const float nm = negm[0] - d;
; #pragma unroll
;         for (int r = 0; r < 16; ++r) { negm[r] = nm; p0[r] -= d; p1[r] -= d; }
;     }
; #pragma unroll
;     for (int r = 0; r < 16; ++r) { p0[r] = __builtin_amdgcn_exp2f(p0[r]); p1[r] = __builtin_amdgcn_exp2f(p1[r]); }
;     float ps = 0.f;
; #pragma unroll
;     for (int r = 0; r < 16; ++r) ps += p0[r];
; #pragma unroll
;     for (int r = 0; r < 16; ++r) ps += p1[r];
;     { auto rr = __builtin_amdgcn_permlane32_swap(__float_as_uint(ps), __float_as_uint(ps), false, false); ps = __uint_as_float(rr[0]) + __uint_as_float(rr[1]); }
;     l_reg = l_reg * alpha + ps;
;     pa0 = pack8(p0, 0); pa1 = pack8(p0, 8); pa2 = pack8(p1, 0); pa3 = pack8(p1, 8);
.LBB0_975:
	v_max3_f32 v48, v64, v65, v66
	v_max3_f32 v49, v67, v68, v69
	v_max3_f32 v50, v70, v71, v72
	v_max3_f32 v48, v48, v73, v74
	v_max3_f32 v49, v49, v75, v76
	v_max3_f32 v50, v50, v77, v78
	v_max3_f32 v48, v48, v79, v80
	v_max3_f32 v49, v49, v81, v82
	v_max3_f32 v50, v50, v83, v84
	v_max3_f32 v48, v48, v85, v86
	v_max3_f32 v49, v49, v87, v88
	v_max3_f32 v50, v50, v89, v90
	v_max3_f32 v48, v48, v91, v92
	v_max3_f32 v49, v49, v93, v94
	v_max3_f32 v48, v48, v49, v50
	v_max_f32_e32 v48, v48, v95
	v_mov_b32_e32 v49, v48
	v_mov_b32_e32 v144, 1.0
	s_nop 0
	v_permlane32_swap_b32_e32 v48, v49
	v_max_f32_e32 v48, v48, v49
	v_cmp_ge_f32_e32 vcc, s94, v48
	s_cmp_eq_u64 vcc, exec
	s_cbranch_scc0 .LBB0_995
.LBB0_977:
	v_exp_f32_e32 v64, v64
	v_exp_f32_e32 v65, v65
	v_exp_f32_e32 v66, v66
	v_exp_f32_e32 v67, v67
	v_add_f32_e32 v51, v64, v65
	v_exp_f32_e32 v68, v68
	v_add_f32_e32 v52, v66, v67
	v_exp_f32_e32 v69, v69
	v_add_f32_e32 v51, v68, v51
	v_exp_f32_e32 v70, v70
	v_add_f32_e32 v52, v69, v52
	v_exp_f32_e32 v71, v71
	v_add_f32_e32 v51, v70, v51
	v_exp_f32_e32 v72, v72
	v_add_f32_e32 v52, v71, v52
	v_exp_f32_e32 v73, v73
	v_add_f32_e32 v51, v72, v51
	v_exp_f32_e32 v74, v74
	v_add_f32_e32 v52, v73, v52
	v_exp_f32_e32 v75, v75
	v_add_f32_e32 v51, v74, v51
	v_exp_f32_e32 v76, v76
	v_add_f32_e32 v52, v75, v52
	v_exp_f32_e32 v77, v77
	v_add_f32_e32 v51, v76, v51
	v_exp_f32_e32 v78, v78
	v_add_f32_e32 v52, v77, v52
	v_exp_f32_e32 v79, v79
	v_add_f32_e32 v51, v78, v51
	v_exp_f32_e32 v80, v80
	v_add_f32_e32 v52, v79, v52
	v_exp_f32_e32 v81, v81
	v_add_f32_e32 v51, v80, v51
	v_exp_f32_e32 v82, v82
	v_add_f32_e32 v52, v81, v52
	v_exp_f32_e32 v83, v83
	v_add_f32_e32 v51, v82, v51
	v_exp_f32_e32 v84, v84
	v_add_f32_e32 v52, v83, v52
	v_exp_f32_e32 v85, v85
	v_add_f32_e32 v51, v84, v51
	v_exp_f32_e32 v86, v86
	v_add_f32_e32 v52, v85, v52
	v_exp_f32_e32 v87, v87
	v_add_f32_e32 v51, v86, v51
	v_exp_f32_e32 v88, v88
	v_add_f32_e32 v52, v87, v52
	v_exp_f32_e32 v89, v89
	v_add_f32_e32 v51, v88, v51
	v_exp_f32_e32 v90, v90
	v_add_f32_e32 v52, v89, v52
	v_exp_f32_e32 v91, v91
	v_add_f32_e32 v51, v90, v51
	v_exp_f32_e32 v92, v92
	v_add_f32_e32 v52, v91, v52
	v_exp_f32_e32 v93, v93
	v_add_f32_e32 v51, v92, v51
	v_exp_f32_e32 v94, v94
	v_add_f32_e32 v52, v93, v52
	v_exp_f32_e32 v95, v95
	v_add_f32_e32 v51, v94, v51
	v_add_f32_e32 v52, v95, v52
	v_cmp_gt_f32_e32 vcc, 1.0, v144
	v_cvt_pk_bf16_f32 v87, v86, v87
	v_cvt_pk_bf16_f32 v86, v84, v85
	v_cvt_pk_bf16_f32 v85, v82, v83
	v_cvt_pk_bf16_f32 v84, v80, v81
	v_cvt_pk_bf16_f32 v82, v92, v93
	v_cvt_pk_bf16_f32 v83, v94, v95
	v_cvt_pk_bf16_f32 v80, v88, v89
	v_cvt_pk_bf16_f32 v81, v90, v91
	v_add_f32_e32 v205, v51, v52
	v_cvt_pk_bf16_f32 v92, v64, v65
	v_cvt_pk_bf16_f32 v93, v66, v67
	v_cvt_pk_bf16_f32 v94, v68, v69
	v_cvt_pk_bf16_f32 v95, v70, v71
	v_cvt_pk_bf16_f32 v88, v72, v73
	v_cvt_pk_bf16_f32 v89, v74, v75
	v_mov_b32_e32 v206, v205
	v_cvt_pk_bf16_f32 v90, v76, v77
	v_cvt_pk_bf16_f32 v91, v78, v79
	v_permlane32_swap_b32_e32 v205, v206
	s_cbranch_vccz .LBB0_981
	s_and_saveexec_b64 s[12:13], s[10:11]
	ds_write_b32 v202, v144 offset:43136
	s_or_b64 exec, exec, s[12:13]
	s_waitcnt lgkmcnt(0)
	v_add_u32_e32 v76, s46, v154
	ds_read_b128 v[64:67], v76 offset:43232
	ds_read_b128 v[68:71], v76 offset:43200
	ds_read_b128 v[72:75], v76 offset:43168
	ds_read_b128 v[76:79], v76 offset:43136
	s_waitcnt lgkmcnt(0)
	s_waitcnt lgkmcnt(3)
	v_pk_mul_f32 v[12:13], v[12:13], v[64:65]
	s_waitcnt lgkmcnt(2)
	v_pk_mul_f32 v[8:9], v[8:9], v[68:69]
	s_waitcnt lgkmcnt(1)
	v_pk_mul_f32 v[4:5], v[4:5], v[72:73]
	v_pk_mul_f32 v[14:15], v[14:15], v[66:67]
	v_pk_mul_f32 v[10:11], v[10:11], v[70:71]
	v_pk_mul_f32 v[6:7], v[6:7], v[74:75]
	s_waitcnt lgkmcnt(0)
	v_pk_mul_f32 v[2:3], v[2:3], v[78:79]
	v_pk_mul_f32 v[0:1], v[0:1], v[76:77]
	v_pk_mul_f32 v[28:29], v[28:29], v[64:65]
	v_pk_mul_f32 v[24:25], v[24:25], v[68:69]
	v_pk_mul_f32 v[20:21], v[20:21], v[72:73]
	v_pk_mul_f32 v[30:31], v[30:31], v[66:67]
	v_pk_mul_f32 v[26:27], v[26:27], v[70:71]
	v_pk_mul_f32 v[22:23], v[22:23], v[74:75]
	v_pk_mul_f32 v[18:19], v[18:19], v[78:79]
	v_pk_mul_f32 v[16:17], v[16:17], v[76:77]
; #define SLOAD(j) do { const size_t krow = (size_t)(seq0 + key0 + 64 * (j) + sr); kst = *(const bf16x8*)(Kp + krow * ldk + sc); vstg = *(const bf16x8*)(Vp + krow * ldk + sc); \
;         if (MODE == 2) { if (tid < 256) pst = *(const bf16x8*)(Kpe + (size_t)(seq0 + key0 + 64 * (j) + pr) * 32 + pc); } } while (0)
; #define SWRITE(b) do { *(bf16x8*)(lds + A_K0 + (b) * A_KBUF + sr * KSTR + sc * 2) = kst; *(bf16x8*)(lds + A_V0 + (b) * A_VBUF + vst) = vstg; \
;         if (MODE == 2) { if (tid < 256) *(bf16x8*)(lds + A_K0 + (b) * A_KBUF + pr * KSTR + 128 + pc * 2) = pst; } } while (0)
; #define SLOAD(S, j) do { const size_t krow = (size_t)(seq0 + 64 * (j) + sr); ks##S = *(const bf16x8*)(Kp + krow * 1024 + sc); vs##S = *(const bf16x8*)(Vp + krow * 1024 + sc); \
;         ps##S = *(const bf16x8*)(Kpe + (size_t)(seq0 + 64 * (j) + pr) * 32 + pc); } while (0)
; #define SWRITE(b, S) do { *(bf16x8*)(lds + A_K0 + (b) * A_KBUF + sr * KSTR + sc * 2) = ks##S; *(bf16x8*)(lds + A_V0 + (b) * A_VBUF + vst) = vs##S; \
;         if (tid < 256) *(bf16x8*)(lds + A_K0 + (b) * A_KBUF + pr * KSTR + 128 + pc * 2) = ps##S; } while (0)
; #define SBAR() __builtin_amdgcn_sched_barrier(0)
; #define SLOAD(S, t) do { const int t_ = (t); if (t_ + 1 < NT) { ks##S = *(const bf16x8*)(Kth + (size_t)(t_ + 1) * 65536); ps##S = *(const bf16x8*)(Pth + (size_t)(t_ + 1) * 2048); } \
;         if (t_ < NT) { vs##S = *(const bf16x8*)(Vth + (size_t)t_ * 65536); } } while (0)
; #define SWRITE(S, t, kw, vw) do { const int t_ = (t); if (t_ + 1 < NT) { *(bf16x8*)((kw) + sr * KSTR + sc * 2) = ks##S; if (tid < 256) *(bf16x8*)((kw) + pr * KSTR + 128 + pc * 2) = ps##S; } \
;         if (t_ < NT) *(bf16x8*)((vw) + vst) = vs##S; } while (0)
; #define HBAR() do { asm volatile("s_waitcnt lgkmcnt(0)" ::: "memory"); __builtin_amdgcn_s_barrier(); asm volatile("" ::: "memory"); } while (0)
; #define SBAR() __builtin_amdgcn_sched_barrier(0)
; __device__ __forceinline__ void mla_unit2(const Params& P, unsigned char* lds, int h, int rb, int grp, bool dry = false) {
;     ...
;         __builtin_amdgcn_s_setprio(0);
;         HBAR();
;         SLOAD(E, i + 2 + hoff); SBAR();
;         mla_qkt_neg(p0, p1, negm, K1, qr, r32, hi);
;         pv_both_kp(o[0], o[1], vb0, pa0, pa1, pa2, pa3);
;         HBAR();
;         __builtin_amdgcn_s_setprio(1);
;         SWRITE(O, i + 1 + hoff, kwO, vwO); SBAR();
.LBB0_981:
	s_setprio 0
	s_waitcnt lgkmcnt(0)
	s_barrier
	s_add_u32 s60, s60, 0x20000
	s_addc_u32 s61, s61, 0
	s_add_u32 s62, s62, 0x20000
	s_addc_u32 s63, s63, 0
	s_add_u32 s64, s64, 0x1000
	s_addc_u32 s65, s65, 0
	s_add_i32 s47, s47, 3
	s_cmp_ge_i32 s47, s54
	s_cbranch_scc1 .LBB0_983
	global_load_dwordx4 v[120:123], v166, s[60:61]
	global_load_dwordx4 v[124:127], v167, s[64:65]
.LBB0_983:
	s_not_b64 s[12:13], s[44:45]
	s_andn2_b64 vcc, exec, s[44:45]
	s_cbranch_vccnz .LBB0_985
	global_load_dwordx4 v[128:131], v166, s[62:63]
.LBB0_985:
	ds_read_b128 v[146:149], v157 offset:13312
	ds_read_b128 v[150:153], v157 offset:13344
	s_waitcnt lgkmcnt(1)
	v_mfma_f32_32x32x16_bf16 v[64:79], v[146:149], v[96:99], v[32:47]
	ds_read_b128 v[146:149], v157 offset:19968
	ds_read_b128 v[162:165], v157 offset:20000
	s_waitcnt lgkmcnt(1)
	v_mfma_f32_32x32x16_bf16 v[48:63], v[146:149], v[96:99], v[32:47]
	v_mfma_f32_32x32x16_bf16 v[64:79], v[150:153], v[100:103], v[64:79]
	ds_read_b128 v[146:149], v157 offset:13376
	ds_read_b128 v[150:153], v157 offset:13408
	s_waitcnt lgkmcnt(2)
	v_mfma_f32_32x32x16_bf16 v[48:63], v[162:165], v[100:103], v[48:63]
	s_waitcnt lgkmcnt(1)
	v_mfma_f32_32x32x16_bf16 v[64:79], v[146:149], v[104:107], v[64:79]
	ds_read_b128 v[146:149], v157 offset:20032
	ds_read_b128 v[162:165], v157 offset:20064
	s_waitcnt lgkmcnt(1)
	v_mfma_f32_32x32x16_bf16 v[48:63], v[146:149], v[104:107], v[48:63]
	v_mfma_f32_32x32x16_bf16 v[64:79], v[150:153], v[108:111], v[64:79]
	ds_read_b128 v[146:149], v157 offset:13440
	ds_read_b128 v[150:153], v157 offset:13472
	s_waitcnt lgkmcnt(2)
	v_mfma_f32_32x32x16_bf16 v[48:63], v[162:165], v[108:111], v[48:63]
	s_waitcnt lgkmcnt(1)
	v_mfma_f32_32x32x16_bf16 v[64:79], v[146:149], v[112:115], v[64:79]
	ds_read_b128 v[146:149], v157 offset:20096
	ds_read_b128 v[162:165], v157 offset:20128
	ds_read_b64_tr_b16 v[168:169], v199 offset:0
	ds_read_b64_tr_b16 v[170:171], v199 offset:0x100
	s_waitcnt lgkmcnt(1)
	v_mfma_f32_32x32x16_bf16 v[48:63], v[146:149], v[112:115], v[48:63]
	ds_read_b64_tr_b16 v[146:147], v199 offset:0x800
	ds_read_b64_tr_b16 v[148:149], v199 offset:0x900
	ds_read_b64_tr_b16 v[182:183], v199 offset:0x1000
	ds_read_b64_tr_b16 v[184:185], v199 offset:0x1100
	ds_read_b64_tr_b16 v[186:187], v199 offset:0x1800
	ds_read_b64_tr_b16 v[188:189], v199 offset:0x1900
	ds_read_b64_tr_b16 v[190:191], v199 offset:0x200
	ds_read_b64_tr_b16 v[192:193], v199 offset:0x300
	v_mfma_f32_32x32x16_bf16 v[64:79], v[150:153], v[116:119], v[64:79]
	ds_read_b64_tr_b16 v[150:151], v199 offset:0xa00
	ds_read_b64_tr_b16 v[152:153], v199 offset:0xb00
	ds_read_b64_tr_b16 v[208:209], v199 offset:0x1200
	ds_read_b64_tr_b16 v[210:211], v199 offset:0x1300
	ds_read_b64_tr_b16 v[212:213], v199 offset:0x1a00
	ds_read_b64_tr_b16 v[214:215], v199 offset:0x1b00
	s_waitcnt lgkmcnt(8)
	s_waitcnt lgkmcnt(0)
	v_mfma_f32_32x32x16_bf16 v[48:63], v[162:165], v[116:119], v[48:63]
	v_mfma_f32_32x32x16_bf16 v[0:15], v[92:95], v[168:171], v[0:15]
	s_waitcnt lgkmcnt(0)
	v_mfma_f32_32x32x16_bf16 v[0:15], v[88:91], v[146:149], v[0:15]
	v_mfma_f32_32x32x16_bf16 v[0:15], v[84:87], v[182:185], v[0:15]
	v_mfma_f32_32x32x16_bf16 v[0:15], v[80:83], v[186:189], v[0:15]
	v_mfma_f32_32x32x16_bf16 v[16:31], v[92:95], v[190:193], v[16:31]
	s_waitcnt lgkmcnt(0)
	s_barrier
	v_mfma_f32_32x32x16_bf16 v[16:31], v[88:91], v[150:153], v[16:31]
	v_mfma_f32_32x32x16_bf16 v[16:31], v[84:87], v[208:211], v[16:31]
	v_mfma_f32_32x32x16_bf16 v[16:31], v[80:83], v[212:215], v[16:31]
	s_setprio 1
	s_cmp_lt_i32 s47, s54
	s_cbranch_scc0 .Lmla_w2_tail
	s_waitcnt vmcnt(5)
	ds_write_b128 v200, v[136:139]
	s_and_saveexec_b64 s[12:13], s[8:9]
	s_cbranch_execz .Lmla_w2_nope
	v_add_u32_e32 v80, v198, v156
	s_waitcnt vmcnt(4)
	ds_write_b128 v80, v[140:143] offset:128
.Lmla_w2_nope:
	s_or_b64 exec, exec, s[12:13]
	s_waitcnt vmcnt(3)
	ds_write_b128 v201, v[132:135] offset:26624
	s_branch .LBB0_991
.Lmla_w2_tail:
	s_and_b64 vcc, exec, s[12:13]
	s_cbranch_vccnz .LBB0_989
	s_waitcnt vmcnt(1)
	ds_write_b128 v200, v[136:139]
	s_and_saveexec_b64 s[12:13], s[8:9]
	s_cbranch_execz .LBB0_988
	v_add_u32_e32 v80, v198, v156
	s_waitcnt vmcnt(0)
	ds_write_b128 v80, v[140:143] offset:128

; __device__ __forceinline__ void mla_softmax_rel_kp(f32x16& p0, f32x16& p1, f32x16& negm, bool first, float& l_reg, float& alpha, bf16x8& pa0, bf16x8& pa1, bf16x8& pa2, bf16x8& pa3) {
;     float pmax = p0[0];
; #pragma unroll
;     for (int r = 1; r < 16; ++r) pmax = fmaxf(pmax, p0[r]);
; #pragma unroll
;     for (int r = 0; r < 16; ++r) pmax = fmaxf(pmax, p1[r]);
;     { auto rr = __builtin_amdgcn_permlane32_swap(__float_as_uint(pmax), __float_as_uint(pmax), false, false); pmax = fmaxf(__uint_as_float(rr[0]), __uint_as_float(rr[1])); }
;     alpha = 1.f;
;     if (__builtin_expect(first || !__all(pmax <= THR2), 0)) {
;         const float d = first ? pmax : fmaxf(pmax, 0.f);
;         if (!first) alpha = __builtin_amdgcn_exp2f(-d);
;         const float nm = negm[0] - d;
; #pragma unroll
;         for (int r = 0; r < 16; ++r) { negm[r] = nm; p0[r] -= d; p1[r] -= d; }
;     }
; #pragma unroll
;     for (int r = 0; r < 16; ++r) { p0[r] = __builtin_amdgcn_exp2f(p0[r]); p1[r] = __builtin_amdgcn_exp2f(p1[r]); }
;     float ps = 0.f;
; #pragma unroll
;     for (int r = 0; r < 16; ++r) ps += p0[r];
; #pragma unroll
;     for (int r = 0; r < 16; ++r) ps += p1[r];
;     { auto rr = __builtin_amdgcn_permlane32_swap(__float_as_uint(ps), __float_as_uint(ps), false, false); ps = __uint_as_float(rr[0]) + __uint_as_float(rr[1]); }
;     l_reg = l_reg * alpha + ps;
;     pa0 = pack8(p0, 0); pa1 = pack8(p0, 8); pa2 = pack8(p1, 0); pa3 = pack8(p1, 8);
.LBB0_991:
	v_max3_f32 v81, v64, v65, v66
	v_max3_f32 v82, v67, v68, v69
	v_max3_f32 v83, v70, v71, v72
	v_max3_f32 v81, v81, v73, v74
	v_max3_f32 v82, v82, v75, v76
	v_max3_f32 v83, v83, v77, v78
	v_max3_f32 v81, v81, v79, v48
	v_max3_f32 v82, v82, v49, v50
	v_max3_f32 v83, v83, v51, v52
	v_max3_f32 v81, v81, v53, v54
	v_max3_f32 v82, v82, v55, v56
	v_max3_f32 v83, v83, v57, v58
	v_max3_f32 v81, v81, v59, v60
	v_max3_f32 v82, v82, v61, v62
	v_max3_f32 v81, v81, v82, v83
	v_max_f32_e32 v81, v81, v63
	v_mov_b32_e32 v82, v81
	v_mov_b32_e32 v80, 1.0
	s_nop 0
	v_permlane32_swap_b32_e32 v81, v82
	v_max_f32_e32 v81, v81, v82
	v_cmp_ge_f32_e32 vcc, s94, v81
	s_cmp_eq_u64 vcc, exec
	s_cbranch_scc0 .LBB0_996
.LBB0_992:
	v_exp_f32_e32 v64, v64
	v_exp_f32_e32 v65, v65
	v_exp_f32_e32 v66, v66
	v_exp_f32_e32 v67, v67
	v_add_f32_e32 v84, v64, v65
	v_exp_f32_e32 v68, v68
	v_add_f32_e32 v85, v66, v67
	v_exp_f32_e32 v69, v69
	v_add_f32_e32 v84, v68, v84
	v_exp_f32_e32 v70, v70
	v_add_f32_e32 v85, v69, v85
	v_exp_f32_e32 v71, v71
	v_add_f32_e32 v84, v70, v84
	v_exp_f32_e32 v72, v72
	v_add_f32_e32 v85, v71, v85
	v_exp_f32_e32 v73, v73
	v_add_f32_e32 v84, v72, v84
	v_exp_f32_e32 v74, v74
	v_add_f32_e32 v85, v73, v85
	v_exp_f32_e32 v75, v75
	v_add_f32_e32 v84, v74, v84
	v_exp_f32_e32 v76, v76
	v_add_f32_e32 v85, v75, v85
	v_exp_f32_e32 v77, v77
	v_add_f32_e32 v84, v76, v84
	v_exp_f32_e32 v78, v78
	v_add_f32_e32 v85, v77, v85
	v_exp_f32_e32 v79, v79
	v_add_f32_e32 v84, v78, v84
	v_exp_f32_e32 v48, v48
	v_add_f32_e32 v85, v79, v85
	v_exp_f32_e32 v49, v49
	v_add_f32_e32 v84, v48, v84
	v_exp_f32_e32 v50, v50
	v_add_f32_e32 v85, v49, v85
	v_exp_f32_e32 v51, v51
	v_add_f32_e32 v84, v50, v84
	v_exp_f32_e32 v52, v52
	v_add_f32_e32 v85, v51, v85
	v_exp_f32_e32 v53, v53
	v_add_f32_e32 v84, v52, v84
	v_exp_f32_e32 v54, v54
	v_add_f32_e32 v85, v53, v85
	v_exp_f32_e32 v55, v55
	v_add_f32_e32 v84, v54, v84
	v_exp_f32_e32 v56, v56
	v_add_f32_e32 v85, v55, v85
	v_exp_f32_e32 v57, v57
	v_add_f32_e32 v84, v56, v84
	v_exp_f32_e32 v58, v58
	v_add_f32_e32 v85, v57, v85
	v_exp_f32_e32 v59, v59
	v_add_f32_e32 v84, v58, v84
	v_exp_f32_e32 v60, v60
	v_add_f32_e32 v85, v59, v85
	v_exp_f32_e32 v61, v61
	v_add_f32_e32 v84, v60, v84
	v_exp_f32_e32 v62, v62
	v_add_f32_e32 v85, v61, v85
	v_exp_f32_e32 v63, v63
	v_add_f32_e32 v84, v62, v84
	v_add_f32_e32 v85, v63, v85
	v_cmp_gt_f32_e32 vcc, 1.0, v80
	v_cvt_pk_bf16_f32 v55, v54, v55
	v_cvt_pk_bf16_f32 v54, v52, v53
	v_cvt_pk_bf16_f32 v52, v48, v49
	v_cvt_pk_bf16_f32 v53, v50, v51
	v_cvt_pk_bf16_f32 v48, v56, v57
	v_cvt_pk_bf16_f32 v49, v58, v59
	v_cvt_pk_bf16_f32 v50, v60, v61
	v_cvt_pk_bf16_f32 v51, v62, v63
	v_cvt_pk_bf16_f32 v60, v64, v65
	v_cvt_pk_bf16_f32 v61, v66, v67
	v_cvt_pk_bf16_f32 v62, v68, v69
	v_cvt_pk_bf16_f32 v63, v70, v71
	v_cvt_pk_bf16_f32 v56, v72, v73
	v_cvt_pk_bf16_f32 v57, v74, v75
	v_cvt_pk_bf16_f32 v58, v76, v77
	v_add_f32_e32 v64, v84, v85
	v_cvt_pk_bf16_f32 v59, v78, v79
	v_mov_b32_e32 v65, v64
	s_nop 1
	v_permlane32_swap_b32_e32 v64, v65
	s_cbranch_vccz .LBB0_964
	s_and_saveexec_b64 s[12:13], s[10:11]
	s_cbranch_execz .LBB0_963
	ds_write_b32 v202, v80 offset:43136
	s_branch .LBB0_963

; __global__ void __launch_bounds__(512, 2) mega_fwd(Params Pk) {
;     extern __shared__ __attribute__((aligned(16))) unsigned char lds[];
	.amdhsa_kernel _Z8mega_fwd6Params
		.amdhsa_group_segment_fixed_size 0
		.amdhsa_private_segment_fixed_size 0
		.amdhsa_kernarg_size 424
		.amdhsa_user_sgpr_count 2
		.amdhsa_user_sgpr_dispatch_ptr 0
		.amdhsa_user_sgpr_queue_ptr 0
		.amdhsa_user_sgpr_kernarg_segment_ptr 1
		.amdhsa_user_sgpr_dispatch_id 0
		.amdhsa_user_sgpr_kernarg_preload_length 0
		.amdhsa_user_sgpr_kernarg_preload_offset 0
		.amdhsa_user_sgpr_private_segment_size 0
		.amdhsa_uses_dynamic_stack 0
		.amdhsa_enable_private_segment 0
		.amdhsa_system_sgpr_workgroup_id_x 1
		.amdhsa_system_sgpr_workgroup_id_y 0
		.amdhsa_system_sgpr_workgroup_id_z 0
		.amdhsa_system_sgpr_workgroup_info 0
		.amdhsa_system_vgpr_workitem_id 2
		.amdhsa_next_free_vgpr 256
		.amdhsa_next_free_sgpr 102
		.amdhsa_accum_offset 256
		.amdhsa_reserve_vcc 1
		.amdhsa_float_round_mode_32 0
		.amdhsa_float_round_mode_16_64 0
		.amdhsa_float_denorm_mode_32 3
		.amdhsa_float_denorm_mode_16_64 3
		.amdhsa_dx10_clamp 1
		.amdhsa_ieee_mode 1
		.amdhsa_fp16_overflow 0
		.amdhsa_tg_split 0
		.amdhsa_exception_fp_ieee_invalid_op 0
		.amdhsa_exception_fp_denorm_src 0
		.amdhsa_exception_fp_ieee_div_zero 0
		.amdhsa_exception_fp_ieee_overflow 0
		.amdhsa_exception_fp_ieee_underflow 0
		.amdhsa_exception_fp_ieee_inexact 0
		.amdhsa_exception_int_div_zero 0
	.end_amdhsa_kernel

; __global__ void __launch_bounds__(512, 2) mega_fwd(Params Pk) {
;     extern __shared__ __attribute__((aligned(16))) unsigned char lds[];
amdhsa.kernels:
  - .agpr_count:     0
    .args:
      - .offset:         0
        .size:           168
        .value_kind:     by_value
      - .offset:         168
        .size:           4
        .value_kind:     hidden_block_count_x
      - .offset:         172
        .size:           4
        .value_kind:     hidden_block_count_y
      - .offset:         176
        .size:           4
        .value_kind:     hidden_block_count_z
      - .offset:         180
        .size:           2
        .value_kind:     hidden_group_size_x
      - .offset:         182
        .size:           2
        .value_kind:     hidden_group_size_y
      - .offset:         184
        .size:           2
        .value_kind:     hidden_group_size_z
      - .offset:         186
        .size:           2
        .value_kind:     hidden_remainder_x
      - .offset:         188
        .size:           2
        .value_kind:     hidden_remainder_y
      - .offset:         190
        .size:           2
        .value_kind:     hidden_remainder_z
      - .offset:         208
        .size:           8
        .value_kind:     hidden_global_offset_x
      - .offset:         216
        .size:           8
        .value_kind:     hidden_global_offset_y
      - .offset:         224
        .size:           8
        .value_kind:     hidden_global_offset_z
      - .offset:         232
        .size:           2
        .value_kind:     hidden_grid_dims
      - .offset:         256
        .size:           8
        .value_kind:     hidden_multigrid_sync_arg
      - .offset:         288
        .size:           4
        .value_kind:     hidden_dynamic_lds_size
    .group_segment_fixed_size: 0
    .kernarg_segment_align: 8
    .kernarg_segment_size: 424
    .language:       OpenCL C
    .language_version:
      - 2
      - 0
    .max_flat_workgroup_size: 512
    .name:           _Z8mega_fwd6Params
    .private_segment_fixed_size: 0
    .sgpr_count:     108
    .sgpr_spill_count: 5
    .symbol:         _Z8mega_fwd6Params.kd
    .uniform_work_group_size: 1
    .uses_dynamic_stack: false
    .vgpr_count:     256
    .vgpr_spill_count: 0
    .wavefront_size: 64
